# up-GEMM K-loop LDS-DMA loads use saddr+32-bit voffset form (no per-load v_lshl_add_u64)
# baseline (speedup 1.0000x reference)
; #define PG8_STAGE(bufoff, gbase, voff) do { _Pragma("unroll") for (int _i = 0; _i < 2; ++_i) \
;         __builtin_amdgcn_global_load_lds((const unsigned*)((const char*)(gbase) + (voff)[_i]), (PG8_LAS unsigned*)(lds + (bufoff) + ldsw + _i * 8192), 16, 0, 0); } while (0)
; #define PG8_LDA(dst, b, h) do { _Pragma("unroll") for (int m = 0; m < 4; ++m) _Pragma("unroll") for (int k = 0; k < 2; ++k) dst[m][k] = *(const PG8_LAS bf16x8*)(lds + PG8_SA(b, h) + aoff + m * 2048 + k * 1024); } while (0)
; #define PG8_LDB(dst, b, h) do { _Pragma("unroll") for (int n = 0; n < 2; ++n) _Pragma("unroll") for (int k = 0; k < 2; ++k) dst[n][k] = *(const PG8_LAS bf16x8*)(lds + PG8_SB(b, h) + boff + n * 2048 + k * 1024); } while (0)
; #define PG8_MMA(ai, bj, At, Bt) do { __builtin_amdgcn_s_setprio(1); _Pragma("unroll") for (int m = 0; m < 4; ++m) _Pragma("unroll") for (int n = 0; n < 2; ++n) _Pragma("unroll") for (int k = 0; k < 2; ++k) \
;         acc[ai][bj][m][n] = __builtin_amdgcn_mfma_f32_16x16x32_bf16(Bt[n][k], At[m][k], acc[ai][bj][m][n], 0, 0, 0); __builtin_amdgcn_s_setprio(0); } while (0)
; #define PG8_WAIT_V(n) asm volatile("s_waitcnt vmcnt(" #n ")" ::: "memory")
; #define PG8_WAIT_L(n) asm volatile("s_waitcnt lgkmcnt(" #n ")" ::: "memory")
; #define PG8_BAR __builtin_amdgcn_s_barrier()
; template <class Epi, class Sched, bool ALIGN_EPI = false, bool SP2 = false>
; __device__ __forceinline__ void gemm_phase(PG8_LAS unsigned char* lds, const Gemm g, const Sched& S, const Epi& E) {
;     ...
;             const char* a1 = cA + (size_t)(t + 1) * kstep;
;             const char* a2 = last ? nA : cA + (size_t)(t + 2) * kstep; const char* b2 = last ? nB : cB + (size_t)(t + 2) * kstep;
;             const char* a3 = a2 + kstep; const char* b3 = b2 + kstep;
;             if (last && has_next) S.a_ready(nxt);
;             if constexpr (SP2) {
;             PG8_LDB(B0, 0, 0); PG8_LDB(B1, 0, 1); PG8_SCHED; PG8_LDA(At, 0, 0); PG8_STAGE(PG8_SA(1, 1), a1 + hstepA, voffA);
;             PG8_WAIT_V(8); PG8_WAIT_L(0); PG8_BAR; PG8_MMA(0, 0, At, B0); PG8_MMA(0, 1, At, B1); PG8_BAR; PG8_SCHED;
;             PG8_LDA(At, 0, 1); PG8_STAGE(PG8_SB(0, 0), b2, voffB); PG8_STAGE(PG8_SB(0, 1), b2 + hstepB, voffB); PG8_STAGE(PG8_SA(0, 0), a2, voffA);
;             PG8_WAIT_V(8); PG8_WAIT_L(0); PG8_BAR; PG8_MMA(1, 0, At, B0); PG8_MMA(1, 1, At, B1); PG8_BAR; PG8_SCHED;
.LBB0_443:
	s_ashr_i32 s21, s20, 31
	s_lshl_b64 s[22:23], s[20:21], 19
	s_add_u32 s22, s56, s22
	s_addc_u32 s23, s57, s23
	s_and_b64 s[50:51], s[8:9], exec
	s_cselect_b32 s21, s23, s67
	s_cselect_b32 s74, s22, s66
	s_ashr_i32 s15, s14, 31
	s_lshl_b64 s[50:51], s[14:15], 19
	s_add_u32 s60, s5, s50
	s_addc_u32 s61, s6, s51
	s_and_b64 s[50:51], s[8:9], exec
	s_cselect_b32 s15, s61, s65
	s_cselect_b32 s75, s60, s64
	s_add_u32 s76, s64, 0x100
	s_addc_u32 s77, s65, 0
	s_add_u32 s64, s66, 0x40080
	s_addc_u32 s65, s67, 0
	s_mov_b32 s78, -2
	s_add_u32 s50, s64, 0xfffc0080
	s_addc_u32 s51, s65, -1
	s_add_i32 s79, 0, 0x10000
	s_cmp_eq_u32 s78, 12
	s_cselect_b32 s69, s21, s51
	s_cselect_b32 s68, s74, s50
	s_cselect_b32 s67, s15, s77
	s_cselect_b32 s66, s75, s76
	s_add_u32 s98, s66, 0x80
	s_addc_u32 s99, s67, 0
	s_add_u32 s100, s68, 0x80
	s_addc_u32 s101, s69, 0
	s_add_i32 s80, 0, 0x14000
	v_add_u32_e32 v156, s79, v143
	v_add_u32_e32 v160, s80, v143
	ds_read_b128 v[138:141], v156
	ds_read_b128 v[148:151], v156 offset:1024
	ds_read_b128 v[152:155], v156 offset:2048
	ds_read_b128 v[156:159], v156 offset:3072
	ds_read_b128 v[188:191], v160
	ds_read_b128 v[192:195], v160 offset:1024
	ds_read_b128 v[196:199], v160 offset:2048
	ds_read_b128 v[200:203], v160 offset:3072
	s_add_i32 m0, s19, 0xc000
	ds_read_b128 v[204:207], v147
	ds_read_b128 v[208:211], v147 offset:1024
	ds_read_b128 v[212:215], v147 offset:2048
	ds_read_b128 v[216:219], v147 offset:3072
	ds_read_b128 v[220:223], v147 offset:4096
	ds_read_b128 v[224:227], v147 offset:5120
	ds_read_b128 v[228:231], v147 offset:6144
	ds_read_b128 v[232:235], v147 offset:7168
	global_load_lds_dwordx4 v136, s[64:65]
	s_add_i32 m0, s19, 0xe000
	s_nop 0
	global_load_lds_dwordx4 v134, s[64:65]
	s_waitcnt vmcnt(8)
	s_waitcnt lgkmcnt(0)
	s_barrier
	s_setprio 1
	s_waitcnt lgkmcnt(0)
	v_mfma_f32_16x16x32_bf16 v[124:127], v[138:141], v[204:207], 0
	v_mfma_f32_16x16x32_bf16 v[116:119], v[152:155], v[204:207], 0
	v_mfma_f32_16x16x32_bf16 v[108:111], v[138:141], v[212:215], 0
	v_mfma_f32_16x16x32_bf16 v[100:103], v[152:155], v[212:215], 0
	v_mfma_f32_16x16x32_bf16 v[92:95], v[138:141], v[220:223], 0
	v_mfma_f32_16x16x32_bf16 v[84:87], v[152:155], v[220:223], 0
	v_mfma_f32_16x16x32_bf16 v[76:79], v[138:141], v[228:231], 0
	v_mfma_f32_16x16x32_bf16 v[68:71], v[152:155], v[228:231], 0
	v_mfma_f32_16x16x32_bf16 v[124:127], v[148:151], v[208:211], v[124:127]
	v_mfma_f32_16x16x32_bf16 v[116:119], v[156:159], v[208:211], v[116:119]
	v_mfma_f32_16x16x32_bf16 v[108:111], v[148:151], v[216:219], v[108:111]
	v_mfma_f32_16x16x32_bf16 v[100:103], v[156:159], v[216:219], v[100:103]
	v_mfma_f32_16x16x32_bf16 v[92:95], v[148:151], v[224:227], v[92:95]
	v_mfma_f32_16x16x32_bf16 v[84:87], v[156:159], v[224:227], v[84:87]
	v_mfma_f32_16x16x32_bf16 v[76:79], v[148:151], v[232:235], v[76:79]
	v_mfma_f32_16x16x32_bf16 v[68:71], v[156:159], v[232:235], v[68:71]
	s_setprio 0
	s_setprio 1
	v_mfma_f32_16x16x32_bf16 v[120:123], v[188:191], v[204:207], 0
	v_mfma_f32_16x16x32_bf16 v[112:115], v[196:199], v[204:207], 0
	v_mfma_f32_16x16x32_bf16 v[104:107], v[188:191], v[212:215], 0
	v_mfma_f32_16x16x32_bf16 v[96:99], v[196:199], v[212:215], 0
	v_mfma_f32_16x16x32_bf16 v[88:91], v[188:191], v[220:223], 0
	v_mfma_f32_16x16x32_bf16 v[80:83], v[196:199], v[220:223], 0
	v_mfma_f32_16x16x32_bf16 v[72:75], v[188:191], v[228:231], 0
	v_mfma_f32_16x16x32_bf16 v[64:67], v[196:199], v[228:231], 0
	v_mfma_f32_16x16x32_bf16 v[120:123], v[192:195], v[208:211], v[120:123]
	v_mfma_f32_16x16x32_bf16 v[112:115], v[200:203], v[208:211], v[112:115]
	v_mfma_f32_16x16x32_bf16 v[104:107], v[192:195], v[216:219], v[104:107]
	v_mfma_f32_16x16x32_bf16 v[96:99], v[200:203], v[216:219], v[96:99]
	v_mfma_f32_16x16x32_bf16 v[88:91], v[192:195], v[224:227], v[88:91]
	v_mfma_f32_16x16x32_bf16 v[80:83], v[200:203], v[224:227], v[80:83]
	v_mfma_f32_16x16x32_bf16 v[72:75], v[192:195], v[232:235], v[72:75]
	v_mfma_f32_16x16x32_bf16 v[64:67], v[200:203], v[232:235], v[64:67]
	s_setprio 0
	s_barrier
	s_add_i32 s50, s79, s7
	s_mov_b32 m0, s50
	ds_read_b128 v[204:207], v147 offset:16384
	ds_read_b128 v[208:211], v147 offset:17408
	ds_read_b128 v[212:215], v147 offset:18432
	ds_read_b128 v[216:219], v147 offset:19456
	ds_read_b128 v[220:223], v147 offset:20480
	ds_read_b128 v[224:227], v147 offset:21504
	ds_read_b128 v[228:231], v147 offset:22528
	ds_read_b128 v[232:235], v147 offset:23552
	global_load_lds_dwordx4 v144, s[66:67]
	s_add_i32 m0, s50, 0x2000
	s_add_u32 s50, s66, 0x40000
	s_addc_u32 s51, s67, 0
	s_add_i32 s79, s80, s7
	global_load_lds_dwordx4 v128, s[66:67]
	s_mov_b32 m0, s79
	s_nop 0
	global_load_lds_dwordx4 v144, s[50:51]
	s_add_i32 m0, s79, 0x2000
	s_nop 0
	global_load_lds_dwordx4 v128, s[50:51]
	s_mov_b32 m0, s19
	s_nop 0
	global_load_lds_dwordx4 v132, s[68:69]
	s_mov_b32 m0, s24
	s_nop 0
	global_load_lds_dwordx4 v130, s[68:69]
	s_waitcnt vmcnt(8)
	s_waitcnt lgkmcnt(0)
	s_barrier
; #define PG8_STAGE(bufoff, gbase, voff) do { _Pragma("unroll") for (int _i = 0; _i < 2; ++_i) \
;         __builtin_amdgcn_global_load_lds((const unsigned*)((const char*)(gbase) + (voff)[_i]), (PG8_LAS unsigned*)(lds + (bufoff) + ldsw + _i * 8192), 16, 0, 0); } while (0)
; #define PG8_LDA(dst, b, h) do { _Pragma("unroll") for (int m = 0; m < 4; ++m) _Pragma("unroll") for (int k = 0; k < 2; ++k) dst[m][k] = *(const PG8_LAS bf16x8*)(lds + PG8_SA(b, h) + aoff + m * 2048 + k * 1024); } while (0)
; #define PG8_LDB(dst, b, h) do { _Pragma("unroll") for (int n = 0; n < 2; ++n) _Pragma("unroll") for (int k = 0; k < 2; ++k) dst[n][k] = *(const PG8_LAS bf16x8*)(lds + PG8_SB(b, h) + boff + n * 2048 + k * 1024); } while (0)
; #define PG8_MMA(ai, bj, At, Bt) do { __builtin_amdgcn_s_setprio(1); _Pragma("unroll") for (int m = 0; m < 4; ++m) _Pragma("unroll") for (int n = 0; n < 2; ++n) _Pragma("unroll") for (int k = 0; k < 2; ++k) \
;         acc[ai][bj][m][n] = __builtin_amdgcn_mfma_f32_16x16x32_bf16(Bt[n][k], At[m][k], acc[ai][bj][m][n], 0, 0, 0); __builtin_amdgcn_s_setprio(0); } while (0)
; #define PG8_WAIT_V(n) asm volatile("s_waitcnt vmcnt(" #n ")" ::: "memory")
; #define PG8_WAIT_L(n) asm volatile("s_waitcnt lgkmcnt(" #n ")" ::: "memory")
; #define PG8_BAR __builtin_amdgcn_s_barrier()
; #define PG8_SCHED __builtin_amdgcn_sched_barrier(0)
; template <class Epi, class Sched, bool ALIGN_EPI = false, bool SP2 = false>
; __device__ __forceinline__ void gemm_phase(PG8_LAS unsigned char* lds, const Gemm g, const Sched& S, const Epi& E) {
;     ...
;             PG8_WAIT_V(8); PG8_WAIT_L(0); PG8_BAR; PG8_MMA(1, 0, At, B0); PG8_MMA(1, 1, At, B1); PG8_BAR; PG8_SCHED;
;             PG8_LDB(B0, 1, 0); PG8_LDB(B1, 1, 1); PG8_SCHED; PG8_LDA(At, 1, 0); PG8_STAGE(PG8_SA(0, 1), a2 + hstepA, voffA);
;             PG8_WAIT_V(8); PG8_WAIT_L(0); PG8_BAR; PG8_MMA(0, 0, At, B0); PG8_MMA(0, 1, At, B1); PG8_BAR; PG8_SCHED;
	s_setprio 1
	s_waitcnt lgkmcnt(0)
	v_mfma_f32_16x16x32_bf16 v[60:63], v[138:141], v[204:207], 0
	v_mfma_f32_16x16x32_bf16 v[52:55], v[152:155], v[204:207], 0
	v_mfma_f32_16x16x32_bf16 v[44:47], v[138:141], v[212:215], 0
	v_mfma_f32_16x16x32_bf16 v[36:39], v[152:155], v[212:215], 0
	v_mfma_f32_16x16x32_bf16 v[28:31], v[138:141], v[220:223], 0
	v_mfma_f32_16x16x32_bf16 v[20:23], v[152:155], v[220:223], 0
	v_mfma_f32_16x16x32_bf16 v[12:15], v[138:141], v[228:231], 0
	v_mfma_f32_16x16x32_bf16 v[4:7], v[152:155], v[228:231], 0
	v_mfma_f32_16x16x32_bf16 v[60:63], v[148:151], v[208:211], v[60:63]
	v_mfma_f32_16x16x32_bf16 v[52:55], v[156:159], v[208:211], v[52:55]
	v_mfma_f32_16x16x32_bf16 v[44:47], v[148:151], v[216:219], v[44:47]
	v_mfma_f32_16x16x32_bf16 v[36:39], v[156:159], v[216:219], v[36:39]
	v_mfma_f32_16x16x32_bf16 v[28:31], v[148:151], v[224:227], v[28:31]
	v_mfma_f32_16x16x32_bf16 v[20:23], v[156:159], v[224:227], v[20:23]
	v_mfma_f32_16x16x32_bf16 v[12:15], v[148:151], v[232:235], v[12:15]
	v_mfma_f32_16x16x32_bf16 v[4:7], v[156:159], v[232:235], v[4:7]
	s_setprio 0
	s_setprio 1
	v_mfma_f32_16x16x32_bf16 v[56:59], v[188:191], v[204:207], 0
	v_mfma_f32_16x16x32_bf16 v[48:51], v[196:199], v[204:207], 0
	v_mfma_f32_16x16x32_bf16 v[40:43], v[188:191], v[212:215], 0
	v_mfma_f32_16x16x32_bf16 v[32:35], v[196:199], v[212:215], 0
	v_mfma_f32_16x16x32_bf16 v[24:27], v[188:191], v[220:223], 0
	v_mfma_f32_16x16x32_bf16 v[16:19], v[196:199], v[220:223], 0
	v_mfma_f32_16x16x32_bf16 v[8:11], v[188:191], v[228:231], 0
	v_mfma_f32_16x16x32_bf16 v[0:3], v[196:199], v[228:231], 0
	v_mfma_f32_16x16x32_bf16 v[56:59], v[192:195], v[208:211], v[56:59]
	v_mfma_f32_16x16x32_bf16 v[48:51], v[200:203], v[208:211], v[48:51]
	v_mfma_f32_16x16x32_bf16 v[40:43], v[192:195], v[216:219], v[40:43]
	v_mfma_f32_16x16x32_bf16 v[32:35], v[200:203], v[216:219], v[32:35]
	v_mfma_f32_16x16x32_bf16 v[24:27], v[192:195], v[224:227], v[24:27]
	v_mfma_f32_16x16x32_bf16 v[16:19], v[200:203], v[224:227], v[16:19]
	v_mfma_f32_16x16x32_bf16 v[8:11], v[192:195], v[232:235], v[8:11]
	v_mfma_f32_16x16x32_bf16 v[0:3], v[200:203], v[232:235], v[0:3]
	s_setprio 0
	s_barrier
	s_add_i32 s79, 0, 0x18000
	s_add_i32 s80, 0, 0x1c000
	v_add_u32_e32 v156, s79, v143
	v_add_u32_e32 v162, s80, v143
	ds_read_b128 v[138:141], v156
	ds_read_b128 v[148:151], v156 offset:1024
	ds_read_b128 v[152:155], v156 offset:2048
	ds_read_b128 v[156:159], v156 offset:3072
	ds_read_b128 v[188:191], v162
	ds_read_b128 v[192:195], v162 offset:1024
	ds_read_b128 v[196:199], v162 offset:2048
	ds_read_b128 v[200:203], v162 offset:3072
	s_add_u32 s50, s68, 0x40000
	s_addc_u32 s51, s69, 0
	s_mov_b32 m0, s25
	ds_read_b128 v[204:207], v147 offset:32768
	ds_read_b128 v[208:211], v147 offset:33792
	ds_read_b128 v[212:215], v147 offset:34816
	ds_read_b128 v[216:219], v147 offset:35840
	ds_read_b128 v[220:223], v147 offset:36864
	ds_read_b128 v[224:227], v147 offset:37888
	ds_read_b128 v[228:231], v147 offset:38912
	ds_read_b128 v[232:235], v147 offset:39936
	global_load_lds_dwordx4 v132, s[50:51]
	s_mov_b32 m0, s31
	s_nop 0
	global_load_lds_dwordx4 v130, s[50:51]
	s_waitcnt vmcnt(8)
	s_waitcnt lgkmcnt(0)
	s_barrier
	s_setprio 1
	s_waitcnt lgkmcnt(0)
	v_mfma_f32_16x16x32_bf16 v[124:127], v[138:141], v[204:207], v[124:127]
	v_mfma_f32_16x16x32_bf16 v[116:119], v[152:155], v[204:207], v[116:119]
	v_mfma_f32_16x16x32_bf16 v[108:111], v[138:141], v[212:215], v[108:111]
	v_mfma_f32_16x16x32_bf16 v[100:103], v[152:155], v[212:215], v[100:103]
	v_mfma_f32_16x16x32_bf16 v[92:95], v[138:141], v[220:223], v[92:95]
	v_mfma_f32_16x16x32_bf16 v[84:87], v[152:155], v[220:223], v[84:87]
	v_mfma_f32_16x16x32_bf16 v[76:79], v[138:141], v[228:231], v[76:79]
	v_mfma_f32_16x16x32_bf16 v[68:71], v[152:155], v[228:231], v[68:71]
	v_mfma_f32_16x16x32_bf16 v[124:127], v[148:151], v[208:211], v[124:127]
	v_mfma_f32_16x16x32_bf16 v[116:119], v[156:159], v[208:211], v[116:119]
	v_mfma_f32_16x16x32_bf16 v[108:111], v[148:151], v[216:219], v[108:111]
	v_mfma_f32_16x16x32_bf16 v[100:103], v[156:159], v[216:219], v[100:103]
	v_mfma_f32_16x16x32_bf16 v[92:95], v[148:151], v[224:227], v[92:95]
	v_mfma_f32_16x16x32_bf16 v[84:87], v[156:159], v[224:227], v[84:87]
	v_mfma_f32_16x16x32_bf16 v[76:79], v[148:151], v[232:235], v[76:79]
	v_mfma_f32_16x16x32_bf16 v[68:71], v[156:159], v[232:235], v[68:71]
	s_setprio 0
	s_setprio 1
	v_mfma_f32_16x16x32_bf16 v[120:123], v[188:191], v[204:207], v[120:123]
	v_mfma_f32_16x16x32_bf16 v[112:115], v[196:199], v[204:207], v[112:115]
	v_mfma_f32_16x16x32_bf16 v[104:107], v[188:191], v[212:215], v[104:107]
	v_mfma_f32_16x16x32_bf16 v[96:99], v[196:199], v[212:215], v[96:99]
	v_mfma_f32_16x16x32_bf16 v[88:91], v[188:191], v[220:223], v[88:91]
	v_mfma_f32_16x16x32_bf16 v[80:83], v[196:199], v[220:223], v[80:83]
	v_mfma_f32_16x16x32_bf16 v[72:75], v[188:191], v[228:231], v[72:75]
	v_mfma_f32_16x16x32_bf16 v[64:67], v[196:199], v[228:231], v[64:67]
	v_mfma_f32_16x16x32_bf16 v[120:123], v[192:195], v[208:211], v[120:123]
	v_mfma_f32_16x16x32_bf16 v[112:115], v[200:203], v[208:211], v[112:115]
	v_mfma_f32_16x16x32_bf16 v[104:107], v[192:195], v[216:219], v[104:107]
	v_mfma_f32_16x16x32_bf16 v[96:99], v[200:203], v[216:219], v[96:99]
	v_mfma_f32_16x16x32_bf16 v[88:91], v[192:195], v[224:227], v[88:91]
	v_mfma_f32_16x16x32_bf16 v[80:83], v[200:203], v[224:227], v[80:83]
	v_mfma_f32_16x16x32_bf16 v[72:75], v[192:195], v[232:235], v[72:75]
	v_mfma_f32_16x16x32_bf16 v[64:67], v[200:203], v[232:235], v[64:67]
	s_setprio 0
	s_barrier
; #define PG8_STAGE(bufoff, gbase, voff) do { _Pragma("unroll") for (int _i = 0; _i < 2; ++_i) \
;         __builtin_amdgcn_global_load_lds((const unsigned*)((const char*)(gbase) + (voff)[_i]), (PG8_LAS unsigned*)(lds + (bufoff) + ldsw + _i * 8192), 16, 0, 0); } while (0)
; #define PG8_LDA(dst, b, h) do { _Pragma("unroll") for (int m = 0; m < 4; ++m) _Pragma("unroll") for (int k = 0; k < 2; ++k) dst[m][k] = *(const PG8_LAS bf16x8*)(lds + PG8_SA(b, h) + aoff + m * 2048 + k * 1024); } while (0)
; #define PG8_MMA(ai, bj, At, Bt) do { __builtin_amdgcn_s_setprio(1); _Pragma("unroll") for (int m = 0; m < 4; ++m) _Pragma("unroll") for (int n = 0; n < 2; ++n) _Pragma("unroll") for (int k = 0; k < 2; ++k) \
;         acc[ai][bj][m][n] = __builtin_amdgcn_mfma_f32_16x16x32_bf16(Bt[n][k], At[m][k], acc[ai][bj][m][n], 0, 0, 0); __builtin_amdgcn_s_setprio(0); } while (0)
; #define PG8_WAIT_V(n) asm volatile("s_waitcnt vmcnt(" #n ")" ::: "memory")
; #define PG8_WAIT_L(n) asm volatile("s_waitcnt lgkmcnt(" #n ")" ::: "memory")
; #define PG8_BAR __builtin_amdgcn_s_barrier()
; #define PG8_SCHED __builtin_amdgcn_sched_barrier(0)
; template <class Epi, class Sched, bool ALIGN_EPI = false, bool SP2 = false>
; __device__ __forceinline__ void gemm_phase(PG8_LAS unsigned char* lds, const Gemm g, const Sched& S, const Epi& E) {
;     ...
;         for (int t = 0; t < nt; t += 2) {
;             const bool last = (t == nt - 2);
;             const char* a1 = cA + (size_t)(t + 1) * kstep;
;             const char* a2 = last ? nA : cA + (size_t)(t + 2) * kstep; const char* b2 = last ? nB : cB + (size_t)(t + 2) * kstep;
;             const char* a3 = a2 + kstep; const char* b3 = b2 + kstep;
;             if (last && has_next) S.a_ready(nxt);
;     ...
;             PG8_LDA(At, 1, 1); PG8_STAGE(PG8_SB(1, 0), b3, voffB); PG8_STAGE(PG8_SB(1, 1), b3 + hstepB, voffB); PG8_STAGE(PG8_SA(1, 0), a3, voffA);
;             PG8_WAIT_V(8); PG8_WAIT_L(0); PG8_BAR; PG8_MMA(1, 0, At, B0); PG8_MMA(1, 1, At, B1); PG8_BAR; PG8_SCHED;
	s_add_i32 s50, s79, s7
	s_mov_b32 m0, s50
	ds_read_b128 v[204:207], v147 offset:49152
	ds_read_b128 v[208:211], v147 offset:50176
	ds_read_b128 v[212:215], v147 offset:51200
	ds_read_b128 v[216:219], v147 offset:52224
	ds_read_b128 v[220:223], v147 offset:53248
	ds_read_b128 v[224:227], v147 offset:54272
	ds_read_b128 v[228:231], v147 offset:55296
	ds_read_b128 v[232:235], v147 offset:56320
	global_load_lds_dwordx4 v144, s[98:99]
	s_add_i32 m0, s50, 0x2000
	s_add_u32 s50, s66, 0x40080
	s_addc_u32 s51, s67, 0
	s_add_i32 s66, s80, s7
	global_load_lds_dwordx4 v128, s[98:99]
	s_mov_b32 m0, s66
	s_nop 0
	global_load_lds_dwordx4 v144, s[50:51]
	s_add_i32 m0, s66, 0x2000
	s_nop 0
	global_load_lds_dwordx4 v128, s[50:51]
	s_mov_b32 m0, s70
	s_nop 0
	global_load_lds_dwordx4 v132, s[100:101]
	s_mov_b32 m0, s71
	s_nop 0
	global_load_lds_dwordx4 v130, s[100:101]
	s_waitcnt vmcnt(8)
	s_waitcnt lgkmcnt(0)
	s_barrier
	s_setprio 1
	s_waitcnt lgkmcnt(0)
	v_mfma_f32_16x16x32_bf16 v[60:63], v[138:141], v[204:207], v[60:63]
	v_mfma_f32_16x16x32_bf16 v[52:55], v[152:155], v[204:207], v[52:55]
	v_mfma_f32_16x16x32_bf16 v[44:47], v[138:141], v[212:215], v[44:47]
	v_mfma_f32_16x16x32_bf16 v[36:39], v[152:155], v[212:215], v[36:39]
	v_mfma_f32_16x16x32_bf16 v[28:31], v[138:141], v[220:223], v[28:31]
	v_mfma_f32_16x16x32_bf16 v[20:23], v[152:155], v[220:223], v[20:23]
	v_mfma_f32_16x16x32_bf16 v[12:15], v[138:141], v[228:231], v[12:15]
	v_mfma_f32_16x16x32_bf16 v[4:7], v[152:155], v[228:231], v[4:7]
	v_mfma_f32_16x16x32_bf16 v[60:63], v[148:151], v[208:211], v[60:63]
	v_mfma_f32_16x16x32_bf16 v[52:55], v[156:159], v[208:211], v[52:55]
	v_mfma_f32_16x16x32_bf16 v[44:47], v[148:151], v[216:219], v[44:47]
	v_mfma_f32_16x16x32_bf16 v[36:39], v[156:159], v[216:219], v[36:39]
	v_mfma_f32_16x16x32_bf16 v[28:31], v[148:151], v[224:227], v[28:31]
	v_mfma_f32_16x16x32_bf16 v[20:23], v[156:159], v[224:227], v[20:23]
	v_mfma_f32_16x16x32_bf16 v[12:15], v[148:151], v[232:235], v[12:15]
	v_mfma_f32_16x16x32_bf16 v[4:7], v[156:159], v[232:235], v[4:7]
	s_setprio 0
	s_setprio 1
	v_mfma_f32_16x16x32_bf16 v[56:59], v[188:191], v[204:207], v[56:59]
	v_mfma_f32_16x16x32_bf16 v[48:51], v[196:199], v[204:207], v[48:51]
	v_mfma_f32_16x16x32_bf16 v[40:43], v[188:191], v[212:215], v[40:43]
	v_mfma_f32_16x16x32_bf16 v[32:35], v[196:199], v[212:215], v[32:35]
	v_mfma_f32_16x16x32_bf16 v[24:27], v[188:191], v[220:223], v[24:27]
	v_mfma_f32_16x16x32_bf16 v[16:19], v[196:199], v[220:223], v[16:19]
	v_mfma_f32_16x16x32_bf16 v[8:11], v[188:191], v[228:231], v[8:11]
	v_mfma_f32_16x16x32_bf16 v[0:3], v[196:199], v[228:231], v[0:3]
	v_mfma_f32_16x16x32_bf16 v[56:59], v[192:195], v[208:211], v[56:59]
	v_mfma_f32_16x16x32_bf16 v[48:51], v[200:203], v[208:211], v[48:51]
	v_mfma_f32_16x16x32_bf16 v[40:43], v[192:195], v[216:219], v[40:43]
	v_mfma_f32_16x16x32_bf16 v[32:35], v[200:203], v[216:219], v[32:35]
	v_mfma_f32_16x16x32_bf16 v[24:27], v[192:195], v[224:227], v[24:27]
	v_mfma_f32_16x16x32_bf16 v[16:19], v[200:203], v[224:227], v[16:19]
	v_mfma_f32_16x16x32_bf16 v[8:11], v[192:195], v[232:235], v[8:11]
	v_mfma_f32_16x16x32_bf16 v[0:3], v[200:203], v[232:235], v[0:3]
	s_setprio 0
	s_barrier
	s_add_i32 s78, s78, 2
	s_add_u32 s76, s76, 0x100
	s_addc_u32 s77, s77, 0
	s_add_u32 s64, s64, 0x100
	s_addc_u32 s65, s65, 0
.LBB0_444:
	s_add_u32 s50, s64, 0xfffc0080
	s_addc_u32 s51, s65, -1
	s_add_i32 s79, 0, 0x10000
	s_cmp_eq_u32 s78, 12
	s_cselect_b32 s69, s21, s51
	s_cselect_b32 s68, s74, s50
	s_cselect_b32 s67, s15, s77
	s_cselect_b32 s66, s75, s76
	s_add_u32 s98, s66, 0x80
	s_addc_u32 s99, s67, 0
	s_add_u32 s100, s68, 0x80
	s_addc_u32 s101, s69, 0
	s_add_i32 s80, 0, 0x14000
	v_add_u32_e32 v156, s79, v143
	v_add_u32_e32 v160, s80, v143
	ds_read_b128 v[138:141], v156
	ds_read_b128 v[148:151], v156 offset:1024
	ds_read_b128 v[152:155], v156 offset:2048
	ds_read_b128 v[156:159], v156 offset:3072
	ds_read_b128 v[188:191], v160
	ds_read_b128 v[192:195], v160 offset:1024
	ds_read_b128 v[196:199], v160 offset:2048
	ds_read_b128 v[200:203], v160 offset:3072
	s_add_i32 m0, s19, 0xc000
	ds_read_b128 v[204:207], v147
	ds_read_b128 v[208:211], v147 offset:1024
	ds_read_b128 v[212:215], v147 offset:2048
	ds_read_b128 v[216:219], v147 offset:3072
	ds_read_b128 v[220:223], v147 offset:4096
	ds_read_b128 v[224:227], v147 offset:5120
	ds_read_b128 v[228:231], v147 offset:6144
	ds_read_b128 v[232:235], v147 offset:7168
	global_load_lds_dwordx4 v136, s[64:65]
	s_add_i32 m0, s19, 0xe000
	s_nop 0
	global_load_lds_dwordx4 v134, s[64:65]
	s_waitcnt vmcnt(8)
	s_waitcnt lgkmcnt(0)
	s_barrier
; #define PG8_STAGE(bufoff, gbase, voff) do { _Pragma("unroll") for (int _i = 0; _i < 2; ++_i) \
;         __builtin_amdgcn_global_load_lds((const unsigned*)((const char*)(gbase) + (voff)[_i]), (PG8_LAS unsigned*)(lds + (bufoff) + ldsw + _i * 8192), 16, 0, 0); } while (0)
; #define PG8_LDA(dst, b, h) do { _Pragma("unroll") for (int m = 0; m < 4; ++m) _Pragma("unroll") for (int k = 0; k < 2; ++k) dst[m][k] = *(const PG8_LAS bf16x8*)(lds + PG8_SA(b, h) + aoff + m * 2048 + k * 1024); } while (0)
; #define PG8_MMA(ai, bj, At, Bt) do { __builtin_amdgcn_s_setprio(1); _Pragma("unroll") for (int m = 0; m < 4; ++m) _Pragma("unroll") for (int n = 0; n < 2; ++n) _Pragma("unroll") for (int k = 0; k < 2; ++k) \
;         acc[ai][bj][m][n] = __builtin_amdgcn_mfma_f32_16x16x32_bf16(Bt[n][k], At[m][k], acc[ai][bj][m][n], 0, 0, 0); __builtin_amdgcn_s_setprio(0); } while (0)
; #define PG8_WAIT_V(n) asm volatile("s_waitcnt vmcnt(" #n ")" ::: "memory")
; #define PG8_WAIT_L(n) asm volatile("s_waitcnt lgkmcnt(" #n ")" ::: "memory")
; #define PG8_BAR __builtin_amdgcn_s_barrier()
; #define PG8_SCHED __builtin_amdgcn_sched_barrier(0)
; template <class Epi, class Sched, bool ALIGN_EPI = false, bool SP2 = false>
; __device__ __forceinline__ void gemm_phase(PG8_LAS unsigned char* lds, const Gemm g, const Sched& S, const Epi& E) {
;     ...
;             PG8_WAIT_V(8); PG8_WAIT_L(0); PG8_BAR; PG8_MMA(0, 0, At, B0); PG8_MMA(0, 1, At, B1); PG8_BAR; PG8_SCHED;
;             PG8_LDA(At, 0, 1); PG8_STAGE(PG8_SB(0, 0), b2, voffB); PG8_STAGE(PG8_SB(0, 1), b2 + hstepB, voffB); PG8_STAGE(PG8_SA(0, 0), a2, voffA);
;             PG8_WAIT_V(8); PG8_WAIT_L(0); PG8_BAR; PG8_MMA(1, 0, At, B0); PG8_MMA(1, 1, At, B1); PG8_BAR; PG8_SCHED;
	s_setprio 1
	s_waitcnt lgkmcnt(0)
	v_mfma_f32_16x16x32_bf16 v[124:127], v[138:141], v[204:207], v[124:127]
	v_mfma_f32_16x16x32_bf16 v[116:119], v[152:155], v[204:207], v[116:119]
	v_mfma_f32_16x16x32_bf16 v[108:111], v[138:141], v[212:215], v[108:111]
	v_mfma_f32_16x16x32_bf16 v[100:103], v[152:155], v[212:215], v[100:103]
	v_mfma_f32_16x16x32_bf16 v[92:95], v[138:141], v[220:223], v[92:95]
	v_mfma_f32_16x16x32_bf16 v[84:87], v[152:155], v[220:223], v[84:87]
	v_mfma_f32_16x16x32_bf16 v[76:79], v[138:141], v[228:231], v[76:79]
	v_mfma_f32_16x16x32_bf16 v[68:71], v[152:155], v[228:231], v[68:71]
	v_mfma_f32_16x16x32_bf16 v[124:127], v[148:151], v[208:211], v[124:127]
	v_mfma_f32_16x16x32_bf16 v[116:119], v[156:159], v[208:211], v[116:119]
	v_mfma_f32_16x16x32_bf16 v[108:111], v[148:151], v[216:219], v[108:111]
	v_mfma_f32_16x16x32_bf16 v[100:103], v[156:159], v[216:219], v[100:103]
	v_mfma_f32_16x16x32_bf16 v[92:95], v[148:151], v[224:227], v[92:95]
	v_mfma_f32_16x16x32_bf16 v[84:87], v[156:159], v[224:227], v[84:87]
	v_mfma_f32_16x16x32_bf16 v[76:79], v[148:151], v[232:235], v[76:79]
	v_mfma_f32_16x16x32_bf16 v[68:71], v[156:159], v[232:235], v[68:71]
	s_setprio 0
	s_setprio 1
	v_mfma_f32_16x16x32_bf16 v[120:123], v[188:191], v[204:207], v[120:123]
	v_mfma_f32_16x16x32_bf16 v[112:115], v[196:199], v[204:207], v[112:115]
	v_mfma_f32_16x16x32_bf16 v[104:107], v[188:191], v[212:215], v[104:107]
	v_mfma_f32_16x16x32_bf16 v[96:99], v[196:199], v[212:215], v[96:99]
	v_mfma_f32_16x16x32_bf16 v[88:91], v[188:191], v[220:223], v[88:91]
	v_mfma_f32_16x16x32_bf16 v[80:83], v[196:199], v[220:223], v[80:83]
	v_mfma_f32_16x16x32_bf16 v[72:75], v[188:191], v[228:231], v[72:75]
	v_mfma_f32_16x16x32_bf16 v[64:67], v[196:199], v[228:231], v[64:67]
	v_mfma_f32_16x16x32_bf16 v[120:123], v[192:195], v[208:211], v[120:123]
	v_mfma_f32_16x16x32_bf16 v[112:115], v[200:203], v[208:211], v[112:115]
	v_mfma_f32_16x16x32_bf16 v[104:107], v[192:195], v[216:219], v[104:107]
	v_mfma_f32_16x16x32_bf16 v[96:99], v[200:203], v[216:219], v[96:99]
	v_mfma_f32_16x16x32_bf16 v[88:91], v[192:195], v[224:227], v[88:91]
	v_mfma_f32_16x16x32_bf16 v[80:83], v[200:203], v[224:227], v[80:83]
	v_mfma_f32_16x16x32_bf16 v[72:75], v[192:195], v[232:235], v[72:75]
	v_mfma_f32_16x16x32_bf16 v[64:67], v[200:203], v[232:235], v[64:67]
	s_setprio 0
	s_barrier
	s_add_i32 s50, s79, s7
	s_mov_b32 m0, s50
	ds_read_b128 v[204:207], v147 offset:16384
	ds_read_b128 v[208:211], v147 offset:17408
	ds_read_b128 v[212:215], v147 offset:18432
	ds_read_b128 v[216:219], v147 offset:19456
	ds_read_b128 v[220:223], v147 offset:20480
	ds_read_b128 v[224:227], v147 offset:21504
	ds_read_b128 v[228:231], v147 offset:22528
	ds_read_b128 v[232:235], v147 offset:23552
	global_load_lds_dwordx4 v144, s[66:67]
	s_add_i32 m0, s50, 0x2000
	s_add_u32 s50, s66, 0x40000
	s_addc_u32 s51, s67, 0
	s_add_i32 s79, s80, s7
	global_load_lds_dwordx4 v128, s[66:67]
	s_mov_b32 m0, s79
	s_nop 0
	global_load_lds_dwordx4 v144, s[50:51]
	s_add_i32 m0, s79, 0x2000
	s_nop 0
	global_load_lds_dwordx4 v128, s[50:51]
	s_mov_b32 m0, s19
	s_nop 0
	global_load_lds_dwordx4 v132, s[68:69]
	s_mov_b32 m0, s24
	s_nop 0
	global_load_lds_dwordx4 v130, s[68:69]
	s_waitcnt vmcnt(8)
	s_waitcnt lgkmcnt(0)
	s_barrier
	s_setprio 1
	s_waitcnt lgkmcnt(0)
	v_mfma_f32_16x16x32_bf16 v[60:63], v[138:141], v[204:207], v[60:63]
	v_mfma_f32_16x16x32_bf16 v[52:55], v[152:155], v[204:207], v[52:55]
	v_mfma_f32_16x16x32_bf16 v[44:47], v[138:141], v[212:215], v[44:47]
	v_mfma_f32_16x16x32_bf16 v[36:39], v[152:155], v[212:215], v[36:39]
	v_mfma_f32_16x16x32_bf16 v[28:31], v[138:141], v[220:223], v[28:31]
	v_mfma_f32_16x16x32_bf16 v[20:23], v[152:155], v[220:223], v[20:23]
	v_mfma_f32_16x16x32_bf16 v[12:15], v[138:141], v[228:231], v[12:15]
	v_mfma_f32_16x16x32_bf16 v[4:7], v[152:155], v[228:231], v[4:7]
	v_mfma_f32_16x16x32_bf16 v[60:63], v[148:151], v[208:211], v[60:63]
	v_mfma_f32_16x16x32_bf16 v[52:55], v[156:159], v[208:211], v[52:55]
	v_mfma_f32_16x16x32_bf16 v[44:47], v[148:151], v[216:219], v[44:47]
	v_mfma_f32_16x16x32_bf16 v[36:39], v[156:159], v[216:219], v[36:39]
	v_mfma_f32_16x16x32_bf16 v[28:31], v[148:151], v[224:227], v[28:31]
	v_mfma_f32_16x16x32_bf16 v[20:23], v[156:159], v[224:227], v[20:23]
	v_mfma_f32_16x16x32_bf16 v[12:15], v[148:151], v[232:235], v[12:15]
	v_mfma_f32_16x16x32_bf16 v[4:7], v[156:159], v[232:235], v[4:7]
	s_setprio 0
	s_setprio 1
	v_mfma_f32_16x16x32_bf16 v[56:59], v[188:191], v[204:207], v[56:59]
	v_mfma_f32_16x16x32_bf16 v[48:51], v[196:199], v[204:207], v[48:51]
	v_mfma_f32_16x16x32_bf16 v[40:43], v[188:191], v[212:215], v[40:43]
	v_mfma_f32_16x16x32_bf16 v[32:35], v[196:199], v[212:215], v[32:35]
	v_mfma_f32_16x16x32_bf16 v[24:27], v[188:191], v[220:223], v[24:27]
	v_mfma_f32_16x16x32_bf16 v[16:19], v[196:199], v[220:223], v[16:19]
	v_mfma_f32_16x16x32_bf16 v[8:11], v[188:191], v[228:231], v[8:11]
	v_mfma_f32_16x16x32_bf16 v[0:3], v[196:199], v[228:231], v[0:3]
	v_mfma_f32_16x16x32_bf16 v[56:59], v[192:195], v[208:211], v[56:59]
	v_mfma_f32_16x16x32_bf16 v[48:51], v[200:203], v[208:211], v[48:51]
	v_mfma_f32_16x16x32_bf16 v[40:43], v[192:195], v[216:219], v[40:43]
	v_mfma_f32_16x16x32_bf16 v[32:35], v[200:203], v[216:219], v[32:35]
	v_mfma_f32_16x16x32_bf16 v[24:27], v[192:195], v[224:227], v[24:27]
	v_mfma_f32_16x16x32_bf16 v[16:19], v[200:203], v[224:227], v[16:19]
	v_mfma_f32_16x16x32_bf16 v[8:11], v[192:195], v[232:235], v[8:11]
	v_mfma_f32_16x16x32_bf16 v[0:3], v[200:203], v[232:235], v[0:3]
	s_setprio 0
	s_barrier
; #define PG8_STAGE(bufoff, gbase, voff) do { _Pragma("unroll") for (int _i = 0; _i < 2; ++_i) \
;         __builtin_amdgcn_global_load_lds((const unsigned*)((const char*)(gbase) + (voff)[_i]), (PG8_LAS unsigned*)(lds + (bufoff) + ldsw + _i * 8192), 16, 0, 0); } while (0)
; #define PG8_LDA(dst, b, h) do { _Pragma("unroll") for (int m = 0; m < 4; ++m) _Pragma("unroll") for (int k = 0; k < 2; ++k) dst[m][k] = *(const PG8_LAS bf16x8*)(lds + PG8_SA(b, h) + aoff + m * 2048 + k * 1024); } while (0)
; #define PG8_LDB(dst, b, h) do { _Pragma("unroll") for (int n = 0; n < 2; ++n) _Pragma("unroll") for (int k = 0; k < 2; ++k) dst[n][k] = *(const PG8_LAS bf16x8*)(lds + PG8_SB(b, h) + boff + n * 2048 + k * 1024); } while (0)
; #define PG8_MMA(ai, bj, At, Bt) do { __builtin_amdgcn_s_setprio(1); _Pragma("unroll") for (int m = 0; m < 4; ++m) _Pragma("unroll") for (int n = 0; n < 2; ++n) _Pragma("unroll") for (int k = 0; k < 2; ++k) \
;         acc[ai][bj][m][n] = __builtin_amdgcn_mfma_f32_16x16x32_bf16(Bt[n][k], At[m][k], acc[ai][bj][m][n], 0, 0, 0); __builtin_amdgcn_s_setprio(0); } while (0)
; #define PG8_WAIT_V(n) asm volatile("s_waitcnt vmcnt(" #n ")" ::: "memory")
; #define PG8_WAIT_L(n) asm volatile("s_waitcnt lgkmcnt(" #n ")" ::: "memory")
; #define PG8_BAR __builtin_amdgcn_s_barrier()
; #define PG8_SCHED __builtin_amdgcn_sched_barrier(0)
; template <class Epi, class Sched, bool ALIGN_EPI = false, bool SP2 = false>
; __device__ __forceinline__ void gemm_phase(PG8_LAS unsigned char* lds, const Gemm g, const Sched& S, const Epi& E) {
;     ...
;         for (int t = 0; t < nt; t += 2) {
;             const bool last = (t == nt - 2);
;             const char* a1 = cA + (size_t)(t + 1) * kstep;
;             const char* a2 = last ? nA : cA + (size_t)(t + 2) * kstep; const char* b2 = last ? nB : cB + (size_t)(t + 2) * kstep;
;     ...
;             PG8_LDB(B0, 1, 0); PG8_LDB(B1, 1, 1); PG8_SCHED; PG8_LDA(At, 1, 0); PG8_STAGE(PG8_SA(0, 1), a2 + hstepA, voffA);
;             PG8_WAIT_V(8); PG8_WAIT_L(0); PG8_BAR; PG8_MMA(0, 0, At, B0); PG8_MMA(0, 1, At, B1); PG8_BAR; PG8_SCHED;
;             PG8_LDA(At, 1, 1); PG8_STAGE(PG8_SB(1, 0), b3, voffB); PG8_STAGE(PG8_SB(1, 1), b3 + hstepB, voffB); PG8_STAGE(PG8_SA(1, 0), a3, voffA);
;             PG8_WAIT_V(8); PG8_WAIT_L(0); PG8_BAR; PG8_MMA(1, 0, At, B0); PG8_MMA(1, 1, At, B1); PG8_BAR; PG8_SCHED;
	s_add_i32 s79, 0, 0x18000
	s_add_i32 s80, 0, 0x1c000
	v_add_u32_e32 v156, s79, v143
	v_add_u32_e32 v162, s80, v143
	ds_read_b128 v[138:141], v156
	ds_read_b128 v[148:151], v156 offset:1024
	ds_read_b128 v[152:155], v156 offset:2048
	ds_read_b128 v[156:159], v156 offset:3072
	ds_read_b128 v[188:191], v162
	ds_read_b128 v[192:195], v162 offset:1024
	ds_read_b128 v[196:199], v162 offset:2048
	ds_read_b128 v[200:203], v162 offset:3072
	s_add_u32 s50, s68, 0x40000
	s_addc_u32 s51, s69, 0
	s_mov_b32 m0, s25
	ds_read_b128 v[204:207], v147 offset:32768
	ds_read_b128 v[208:211], v147 offset:33792
	ds_read_b128 v[212:215], v147 offset:34816
	ds_read_b128 v[216:219], v147 offset:35840
	ds_read_b128 v[220:223], v147 offset:36864
	ds_read_b128 v[224:227], v147 offset:37888
	ds_read_b128 v[228:231], v147 offset:38912
	ds_read_b128 v[232:235], v147 offset:39936
	global_load_lds_dwordx4 v132, s[50:51]
	s_mov_b32 m0, s31
	s_nop 0
	global_load_lds_dwordx4 v130, s[50:51]
	s_waitcnt vmcnt(8)
	s_waitcnt lgkmcnt(0)
	s_barrier
	s_setprio 1
	s_waitcnt lgkmcnt(0)
	v_mfma_f32_16x16x32_bf16 v[124:127], v[138:141], v[204:207], v[124:127]
	v_mfma_f32_16x16x32_bf16 v[116:119], v[152:155], v[204:207], v[116:119]
	v_mfma_f32_16x16x32_bf16 v[108:111], v[138:141], v[212:215], v[108:111]
	v_mfma_f32_16x16x32_bf16 v[100:103], v[152:155], v[212:215], v[100:103]
	v_mfma_f32_16x16x32_bf16 v[92:95], v[138:141], v[220:223], v[92:95]
	v_mfma_f32_16x16x32_bf16 v[84:87], v[152:155], v[220:223], v[84:87]
	v_mfma_f32_16x16x32_bf16 v[76:79], v[138:141], v[228:231], v[76:79]
	v_mfma_f32_16x16x32_bf16 v[68:71], v[152:155], v[228:231], v[68:71]
	v_mfma_f32_16x16x32_bf16 v[124:127], v[148:151], v[208:211], v[124:127]
	v_mfma_f32_16x16x32_bf16 v[116:119], v[156:159], v[208:211], v[116:119]
	v_mfma_f32_16x16x32_bf16 v[108:111], v[148:151], v[216:219], v[108:111]
	v_mfma_f32_16x16x32_bf16 v[100:103], v[156:159], v[216:219], v[100:103]
	v_mfma_f32_16x16x32_bf16 v[92:95], v[148:151], v[224:227], v[92:95]
	v_mfma_f32_16x16x32_bf16 v[84:87], v[156:159], v[224:227], v[84:87]
	v_mfma_f32_16x16x32_bf16 v[76:79], v[148:151], v[232:235], v[76:79]
	v_mfma_f32_16x16x32_bf16 v[68:71], v[156:159], v[232:235], v[68:71]
	s_setprio 0
	s_setprio 1
	v_mfma_f32_16x16x32_bf16 v[120:123], v[188:191], v[204:207], v[120:123]
	v_mfma_f32_16x16x32_bf16 v[112:115], v[196:199], v[204:207], v[112:115]
	v_mfma_f32_16x16x32_bf16 v[104:107], v[188:191], v[212:215], v[104:107]
	v_mfma_f32_16x16x32_bf16 v[96:99], v[196:199], v[212:215], v[96:99]
	v_mfma_f32_16x16x32_bf16 v[88:91], v[188:191], v[220:223], v[88:91]
	v_mfma_f32_16x16x32_bf16 v[80:83], v[196:199], v[220:223], v[80:83]
	v_mfma_f32_16x16x32_bf16 v[72:75], v[188:191], v[228:231], v[72:75]
	v_mfma_f32_16x16x32_bf16 v[64:67], v[196:199], v[228:231], v[64:67]
	v_mfma_f32_16x16x32_bf16 v[120:123], v[192:195], v[208:211], v[120:123]
	v_mfma_f32_16x16x32_bf16 v[112:115], v[200:203], v[208:211], v[112:115]
	v_mfma_f32_16x16x32_bf16 v[104:107], v[192:195], v[216:219], v[104:107]
	v_mfma_f32_16x16x32_bf16 v[96:99], v[200:203], v[216:219], v[96:99]
	v_mfma_f32_16x16x32_bf16 v[88:91], v[192:195], v[224:227], v[88:91]
	v_mfma_f32_16x16x32_bf16 v[80:83], v[200:203], v[224:227], v[80:83]
	v_mfma_f32_16x16x32_bf16 v[72:75], v[192:195], v[232:235], v[72:75]
	v_mfma_f32_16x16x32_bf16 v[64:67], v[200:203], v[232:235], v[64:67]
	s_setprio 0
	s_barrier
	s_add_i32 s50, s79, s7
	s_mov_b32 m0, s50
	ds_read_b128 v[204:207], v147 offset:49152
	ds_read_b128 v[208:211], v147 offset:50176
	ds_read_b128 v[212:215], v147 offset:51200
	ds_read_b128 v[216:219], v147 offset:52224
	ds_read_b128 v[220:223], v147 offset:53248
	ds_read_b128 v[224:227], v147 offset:54272
	ds_read_b128 v[228:231], v147 offset:55296
	ds_read_b128 v[232:235], v147 offset:56320
	global_load_lds_dwordx4 v144, s[98:99]
	s_add_i32 m0, s50, 0x2000
	s_add_u32 s50, s66, 0x40080
	s_addc_u32 s51, s67, 0
	s_add_i32 s66, s80, s7
	global_load_lds_dwordx4 v128, s[98:99]
	s_mov_b32 m0, s66
	s_nop 0
	global_load_lds_dwordx4 v144, s[50:51]
	s_add_i32 m0, s66, 0x2000
	s_nop 0
	global_load_lds_dwordx4 v128, s[50:51]
	s_mov_b32 m0, s70
	s_nop 0
	global_load_lds_dwordx4 v132, s[100:101]
	s_mov_b32 m0, s71
	s_nop 0
	global_load_lds_dwordx4 v130, s[100:101]
	s_waitcnt vmcnt(8)
	s_waitcnt lgkmcnt(0)
	s_barrier
	s_setprio 1
	s_waitcnt lgkmcnt(0)
	v_mfma_f32_16x16x32_bf16 v[60:63], v[138:141], v[204:207], v[60:63]
	v_mfma_f32_16x16x32_bf16 v[52:55], v[152:155], v[204:207], v[52:55]
	v_mfma_f32_16x16x32_bf16 v[44:47], v[138:141], v[212:215], v[44:47]
	v_mfma_f32_16x16x32_bf16 v[36:39], v[152:155], v[212:215], v[36:39]
	v_mfma_f32_16x16x32_bf16 v[28:31], v[138:141], v[220:223], v[28:31]
	v_mfma_f32_16x16x32_bf16 v[20:23], v[152:155], v[220:223], v[20:23]
	v_mfma_f32_16x16x32_bf16 v[12:15], v[138:141], v[228:231], v[12:15]
	v_mfma_f32_16x16x32_bf16 v[4:7], v[152:155], v[228:231], v[4:7]
	v_mfma_f32_16x16x32_bf16 v[60:63], v[148:151], v[208:211], v[60:63]
	v_mfma_f32_16x16x32_bf16 v[52:55], v[156:159], v[208:211], v[52:55]
	v_mfma_f32_16x16x32_bf16 v[44:47], v[148:151], v[216:219], v[44:47]
	v_mfma_f32_16x16x32_bf16 v[36:39], v[156:159], v[216:219], v[36:39]
	v_mfma_f32_16x16x32_bf16 v[28:31], v[148:151], v[224:227], v[28:31]
	v_mfma_f32_16x16x32_bf16 v[20:23], v[156:159], v[224:227], v[20:23]
	v_mfma_f32_16x16x32_bf16 v[12:15], v[148:151], v[232:235], v[12:15]
	v_mfma_f32_16x16x32_bf16 v[4:7], v[156:159], v[232:235], v[4:7]
	s_setprio 0
	s_setprio 1
	v_mfma_f32_16x16x32_bf16 v[56:59], v[188:191], v[204:207], v[56:59]
	v_mfma_f32_16x16x32_bf16 v[48:51], v[196:199], v[204:207], v[48:51]
	v_mfma_f32_16x16x32_bf16 v[40:43], v[188:191], v[212:215], v[40:43]
	v_mfma_f32_16x16x32_bf16 v[32:35], v[196:199], v[212:215], v[32:35]
	v_mfma_f32_16x16x32_bf16 v[24:27], v[188:191], v[220:223], v[24:27]
	v_mfma_f32_16x16x32_bf16 v[16:19], v[196:199], v[220:223], v[16:19]
	v_mfma_f32_16x16x32_bf16 v[8:11], v[188:191], v[228:231], v[8:11]
	v_mfma_f32_16x16x32_bf16 v[0:3], v[196:199], v[228:231], v[0:3]
	v_mfma_f32_16x16x32_bf16 v[56:59], v[192:195], v[208:211], v[56:59]
	v_mfma_f32_16x16x32_bf16 v[48:51], v[200:203], v[208:211], v[48:51]
	v_mfma_f32_16x16x32_bf16 v[40:43], v[192:195], v[216:219], v[40:43]
	v_mfma_f32_16x16x32_bf16 v[32:35], v[200:203], v[216:219], v[32:35]
	v_mfma_f32_16x16x32_bf16 v[24:27], v[192:195], v[224:227], v[24:27]
	v_mfma_f32_16x16x32_bf16 v[16:19], v[200:203], v[224:227], v[16:19]
	v_mfma_f32_16x16x32_bf16 v[8:11], v[192:195], v[232:235], v[8:11]
	v_mfma_f32_16x16x32_bf16 v[0:3], v[200:203], v[232:235], v[0:3]
	s_setprio 0
	s_barrier
	s_add_i32 s78, s78, 2
	s_add_u32 s76, s76, 0x100
	s_addc_u32 s77, s77, 0
	s_add_u32 s64, s64, 0x100
	s_addc_u32 s65, s65, 0
	s_cmp_gt_u32 s78, 13
	s_cbranch_scc0 .LBB0_444
	s_and_b64 vcc, exec, s[12:13]
	s_cbranch_vccz .LBB0_447
	s_barrier
